# NSA selected branch: per-wave block-selected test and K-fragment LDS reads moved to the top of the key-block iteration (conditional)
# baseline (speedup 1.0000x reference)
; DI void nsa_item(const Params& p, int bk, int qb, char* smem, float Mb) {
;     ...
;             const unsigned sub = (unsigned)(m >> (wave * 16)) & 0xffffu;
;             if (sub) {
;                 const char* kb_ = tb + bsel * 18432 + fr * 144 + fq * 16;
;                 bf16x8 kf[4][2], vf[4][2];
; #pragma unroll
;                 for (int k4 = 0; k4 < 4; ++k4) {
;                     kf[k4][0] = *(const bf16x8*)(kb_ + k4 * 16 * 144); kf[k4][1] = *(const bf16x8*)(kb_ + k4 * 16 * 144 + 64);
;                     vf[k4][0] = *(const bf16x8*)(kb_ + 9216 + k4 * 16 * 144); vf[k4][1] = *(const bf16x8*)(kb_ + 9216 + k4 * 16 * 144 + 64);
.LBB0_535:
	v_lshrrev_b64 v[88:89], s93, v[88:89]
	v_cmp_ne_u32_sdwa s[100:101], v88, v189 src0_sel:WORD_0 src1_sel:DWORD
	s_nop 3
	s_and_b64 s[6:7], exec, s[100:101]
	s_cbranch_scc0 .Lsel_nok
	s_mul_i32 s6, s22, 0x4800
	v_add_u32_e32 v116, s6, v239
	ds_read_b128 v[120:123], v116
	ds_read_b128 v[128:131], v116 offset:64
	ds_read_b128 v[132:135], v116 offset:2304
	ds_read_b128 v[136:139], v116 offset:2368
	ds_read_b128 v[144:147], v116 offset:4608
	ds_read_b128 v[148:151], v116 offset:4672
	ds_read_b128 v[152:155], v116 offset:6912

; DI void nsa_item(const Params& p, int bk, int qb, char* smem, float Mb) {
;     ...
;                 const bf16_t* src = ((i >> 1) ? VS : KS) + (size_t)j * 4096 + (l_row + 32 * (i & 1)) * 64 + l_cc * 8;
;                 rg[i] = *(const u32x4*)src;
;     ...
;             const int jn = next_valid(j + 1, mn);
;             gload(jn <= cur ? jn : j);
;             const unsigned sub = (unsigned)(m >> (wave * 16)) & 0xffffu;
;             if (sub) {
;                 const char* kb_ = tb + bsel * 18432 + fr * 144 + fq * 16;
;                 bf16x8 kf[4][2], vf[4][2];
; #pragma unroll
;                 for (int k4 = 0; k4 < 4; ++k4) {
;                     kf[k4][0] = *(const bf16x8*)(kb_ + k4 * 16 * 144); kf[k4][1] = *(const bf16x8*)(kb_ + k4 * 16 * 144 + 64);
;                     vf[k4][0] = *(const bf16x8*)(kb_ + 9216 + k4 * 16 * 144); vf[k4][1] = *(const bf16x8*)(kb_ + 9216 + k4 * 16 * 144 + 64);
;                 }
;                 const bool mine = (sub >> fr) & 1u;
;                 const float Ml = mine ? Mb : 3.0e38f;
;                 const bool diag = (j == cur);
; #pragma unroll
;                 for (int g = 0; g < 3; ++g) {
;                     f32x4 st[4];
;                     st_from(kf, qf[g], st, -Ml);
;                     if (diag) {
; #pragma unroll
;                         for (int k4 = 0; k4 < 4; ++k4)
; #pragma unroll
;                             for (int ii = 0; ii < 4; ++ii) {
;                                 const float pv = (j * 64 + k4 * 16 + fq * 4 + ii <= tq) ? __builtin_amdgcn_exp2f(st[k4][ii]) : 0.f;
;                                 st[k4][ii] = pv; ls[g] += pv;
;                             }
;                     } else {
; #pragma unroll
;                         for (int k4 = 0; k4 < 4; ++k4)
; #pragma unroll
;                             for (int ii = 0; ii < 4; ++ii) { const float pv = __builtin_amdgcn_exp2f(st[k4][ii]); st[k4][ii] = pv; ls[g] += pv; }
.LBB0_546:
	s_or_b64 exec, exec, s[8:9]
	v_cmp_gt_i32_e64 s[4:5], v242, v238
	v_mov_b32_e32 v207, v189
	v_mov_b32_e32 v205, v189
	v_cndmask_b32_e64 v72, v242, v245, s[4:5]
	v_lshlrev_b32_e32 v72, 13, v72
	v_add3_u32 v254, v72, v188, v204
	v_add3_u32 v255, v72, v206, v204
	global_load_dwordx4 v[72:75], v254, s[50:51]
	global_load_dwordx4 v[76:79], v255, s[50:51]
	global_load_dwordx4 v[80:83], v254, s[36:37]
	global_load_dwordx4 v[84:87], v255, s[36:37]
	s_and_saveexec_b64 s[12:13], s[100:101]
	s_cbranch_execz .LBB0_534
	v_and_b32_e32 v88, v240, v88
	v_cmp_ne_u32_e64 s[6:7], 0, v88
	s_nop 1
	v_cndmask_b32_e64 v124, v229, v235, s[6:7]
	v_mov_b32_e32 v125, v124
	v_mov_b32_e32 v126, v124
	v_mov_b32_e32 v127, v124
	v_cmp_ne_u32_e64 s[6:7], v245, v238
	s_nop 3
	s_and_b64 s[8:9], exec, s[6:7]
	s_cbranch_scc1 .Lsel_fast
	s_waitcnt lgkmcnt(4)
	v_mfma_f32_16x16x32_bf16 v[92:95], v[132:135], v[0:3], v[124:127]
	v_mfma_f32_16x16x32_bf16 v[88:91], v[120:123], v[0:3], v[124:127]
	s_waitcnt lgkmcnt(3)
	v_mfma_f32_16x16x32_bf16 v[176:179], v[136:139], v[4:7], v[92:95]
	s_waitcnt lgkmcnt(2)
	v_mfma_f32_16x16x32_bf16 v[92:95], v[144:147], v[0:3], v[124:127]
	v_mfma_f32_16x16x32_bf16 v[184:187], v[128:131], v[4:7], v[88:91]
	ds_read_b128 v[108:111], v116 offset:9216
	s_nop 1
	ds_read_b128 v[88:91], v116 offset:9280
	ds_read_b128 v[140:143], v116 offset:6976
	s_waitcnt lgkmcnt(3)
	v_mfma_f32_16x16x32_bf16 v[156:159], v[152:155], v[0:3], v[124:127]
	v_mfma_f32_16x16x32_bf16 v[168:171], v[148:151], v[4:7], v[92:95]
	s_nop 2
	ds_read_b128 v[92:95], v116 offset:11520
	ds_read_b128 v[96:99], v116 offset:11584
	ds_read_b128 v[100:103], v116 offset:13824
	ds_read_b128 v[104:107], v116 offset:13888
	ds_read_b128 v[112:115], v116 offset:16128
	ds_read_b128 v[116:119], v116 offset:16192
	s_waitcnt lgkmcnt(6)
	v_mfma_f32_16x16x32_bf16 v[160:163], v[140:143], v[4:7], v[156:159]
	s_and_saveexec_b64 s[8:9], s[6:7]
	s_xor_b64 s[8:9], exec, s[8:9]
	s_cbranch_execz .LBB0_549
	v_exp_f32_e32 v156, v184
	v_exp_f32_e32 v157, v185
	v_exp_f32_e32 v158, v186
	v_exp_f32_e32 v159, v187
	v_exp_f32_e32 v164, v176
	v_exp_f32_e32 v165, v177
	v_exp_f32_e32 v166, v178
	v_exp_f32_e32 v167, v179
	v_exp_f32_e32 v172, v168
	v_exp_f32_e32 v173, v169
	v_exp_f32_e32 v174, v170
	v_exp_f32_e32 v175, v171
	v_exp_f32_e32 v180, v160
	v_exp_f32_e32 v181, v161
	v_exp_f32_e32 v182, v162
	v_exp_f32_e32 v183, v163
	v_pk_add_f32 v[184:185], v[156:157], v[158:159]
	v_pk_add_f32 v[186:187], v[164:165], v[166:167]
	v_pk_add_f32 v[176:177], v[172:173], v[174:175]
	v_pk_add_f32 v[178:179], v[180:181], v[182:183]
	v_pk_add_f32 v[184:185], v[184:185], v[186:187]
	v_pk_add_f32 v[176:177], v[176:177], v[178:179]
	v_pk_add_f32 v[184:185], v[184:185], v[176:177]
	v_add_f32_e32 v244, v244, v184
	v_add_f32_e32 v244, v244, v185
